# P3b gate-in-place epilogue: the attention-output rows are requested before the silu staging (3 of 4 groups up front, 4th after the first store) instead of four dependent load-wait-use groups
# speedup vs baseline: 1.0373x; 1.0043x over previous
; DI unsigned pk2(float lo, float hi) { f32x2 v = {lo, hi}; bf2_t b = __builtin_convertvector(v, bf2_t); return __builtin_bit_cast(unsigned, b); }
; DI u32x2 pk4(float a, float b, float c, float d) { u32x2 r; r.x = pk2(a, b); r.y = pk2(c, d); return r; }
; DI float bf_lo(unsigned u) { return __uint_as_float(u << 16); }
; DI float bf_hi(unsigned u) { return __uint_as_float(u & 0xffff0000u); }
; DI float fsilu(float z) { return z * fsigmoid(z); }
; template <int WI, int WGJ, class GetF, class LdF, class FinF>
; DI void staged_rows_rmw(unsigned char* lds, int tid, GetF get, LdF ld, FinF fin) {
;     ...
;         unsigned char* wrow = lds + (wj * 32 + ln) * RS + (wi * WI * 32 + 4 * h) * 2;
; #pragma unroll
;         for (int it = 0; it < WI; ++it)
; #pragma unroll
;             for (int g = 0; g < 4; ++g) *(u32x2*)(wrow + (it * 32 + 8 * g) * 2) = get(it, jt, g);
;         constexpr int NGRP = 2, GSZ = NIT / NGRP;
;         __syncthreads();
; DI void phase3b(const Params& p, unsigned char* smem, int tid) {
;     ...
;         if (half == 0) {
;             bf16_t* obuf = (bf16_t*)(ws + (f < 4 ? OFF_QN : OFF_FQ)) + (f & 3) * 256;
;             staged_rows_rmw<4, 4>(lds, te,
;                 [&](int it, int jt, int g) { const float sc = rsj[jt];
;                     return pk4(fsilu(acc[it][jt][4 * g] * sc), fsilu(acc[it][jt][4 * g + 1] * sc), fsilu(acc[it][jt][4 * g + 2] * sc), fsilu(acc[it][jt][4 * g + 3] * sc)); },
;                 [&](int row, int col) { return *(const u32x4*)(obuf + (size_t)(r0 + row) * 1024 + col); },
;                 [&](int row, int col, u32x4 v, u32x4 o) { u32x4 w;
; #pragma unroll
;                     for (int e = 0; e < 4; ++e) w[e] = pk2(bf_lo(o[e]) * bf_lo(v[e]), bf_hi(o[e]) * bf_hi(v[e]));
;                     *(u32x4*)(obuf + (size_t)(r0 + row) * 1024 + col) = w; });
.LBB0_928:
	s_andn2_b64 vcc, exec, s[22:23]
	s_cbranch_vccnz .LBB0_912
	s_cmp_lt_u32 s25, 4
	s_cselect_b32 s98, s36, 0x398fc00
	s_lshr_b32 s99, s24, 2
	s_lshl_b32 s99, s99, 9
	s_and_b32 s99, s99, 0x600
	s_add_u32 s98, s98, s99
	s_add_u32 s100, s56, s98
	s_addc_u32 s101, s57, 0
	v_lshrrev_b32_e32 v196, 5, v177
	v_add_u32_e32 v196, s26, v196
	v_lshlrev_b32_e32 v196, 11, v196
	v_and_b32_e32 v197, 31, v177
	v_lshl_add_u32 v196, v197, 4, v196
	v_lshrrev_b32_e32 v244, 5, v177
	v_mul_u32_u24_e32 v244, 0x210, v244
	v_lshl_add_u32 v197, v197, 4, v244
	global_load_dwordx4 v[188:191], v196, s[100:101]
	v_add_u32_e32 v245, 0x8000, v196
	global_load_dwordx4 v[192:195], v245, s[100:101]
	v_add_u32_e32 v244, 0x20000, v196
	global_load_dwordx4 v[200:203], v244, s[100:101]
	v_add_u32_e32 v245, 0x28000, v196
	global_load_dwordx4 v[204:207], v245, s[100:101]
	v_add_u32_e32 v244, 0x40000, v196
	global_load_dwordx4 v[208:211], v244, s[100:101]
	v_add_u32_e32 v245, 0x48000, v196
	global_load_dwordx4 v[212:215], v245, s[100:101]
	v_add_u32_e32 v244, 0x60000, v196
	global_load_dwordx4 v[216:219], v244, s[100:101]
	v_add_u32_e32 v245, 0x68000, v196
	global_load_dwordx4 v[220:223], v245, s[100:101]
	v_add_u32_e32 v244, 0x10000, v196
	global_load_dwordx4 v[224:227], v244, s[100:101]
	v_add_u32_e32 v245, 0x18000, v196
	global_load_dwordx4 v[228:231], v245, s[100:101]
	v_add_u32_e32 v244, 0x30000, v196
	global_load_dwordx4 v[232:235], v244, s[100:101]
	v_add_u32_e32 v245, 0x38000, v196
	global_load_dwordx4 v[236:239], v245, s[100:101]
	v_lshrrev_b32_e32 v181, 30, v181
	v_add_u32_e32 v181, v180, v181
	v_and_b32_e32 v182, 0x7ffffc, v181
	v_sub_u32_e32 v180, v180, v182
	v_lshl_or_b32 v179, v180, 5, v179
	v_lshlrev_b32_e32 v180, 6, v181
	v_mul_lo_u32 v179, v179, s37
	v_and_b32_e32 v180, 0xffffff00, v180
	v_add3_u32 v179, 0, v179, v180
	s_waitcnt vmcnt(13)
	v_pk_mul_f32 v[112:113], v[112:113], v[178:179] op_sel_hi:[1,0]
	v_lshrrev_b32_e32 v181, 2, v177
	v_mul_f32_e32 v180, 0xbfb8aa3b, v112
	v_mul_f32_e32 v182, 0xbfb8aa3b, v113
	v_exp_f32_e32 v180, v180
	v_exp_f32_e32 v182, v182
	v_and_b32_e32 v181, 8, v181
	v_add_u32_e32 v179, v179, v181
	v_pk_mul_f32 v[114:115], v[114:115], v[178:179] op_sel_hi:[1,0]
	v_add_f32_e32 v180, 1.0, v180
	v_add_f32_e32 v181, 1.0, v182
	v_mul_f32_e32 v182, 0xbfb8aa3b, v114
	v_mul_f32_e32 v183, 0xbfb8aa3b, v115
	v_rcp_f32_e32 v180, v180
	v_rcp_f32_e32 v181, v181
	v_exp_f32_e32 v182, v182
	v_exp_f32_e32 v183, v183
	v_pk_mul_f32 v[116:117], v[116:117], v[178:179] op_sel_hi:[1,0]
	v_pk_mul_f32 v[112:113], v[112:113], v[180:181]
	v_add_f32_e32 v180, 1.0, v182
	v_add_f32_e32 v181, 1.0, v183
	v_mul_f32_e32 v182, 0xbfb8aa3b, v116
	v_mul_f32_e32 v183, 0xbfb8aa3b, v117
	v_rcp_f32_e32 v180, v180
	v_rcp_f32_e32 v181, v181
	v_exp_f32_e32 v182, v182
	v_exp_f32_e32 v183, v183
	v_pk_mul_f32 v[118:119], v[118:119], v[178:179] op_sel_hi:[1,0]
	v_pk_mul_f32 v[114:115], v[114:115], v[180:181]
	v_add_f32_e32 v180, 1.0, v182
	v_add_f32_e32 v181, 1.0, v183
	v_mul_f32_e32 v182, 0xbfb8aa3b, v118
	v_mul_f32_e32 v183, 0xbfb8aa3b, v119
	v_exp_f32_e32 v182, v182
	v_exp_f32_e32 v183, v183
	v_rcp_f32_e32 v180, v180
	v_rcp_f32_e32 v181, v181
	v_add_f32_e32 v182, 1.0, v182
	v_add_f32_e32 v183, 1.0, v183
	v_rcp_f32_e32 v182, v182
	v_rcp_f32_e32 v183, v183
	v_cvt_pk_bf16_f32 v187, v114, v115
	v_cvt_pk_bf16_f32 v186, v112, v113
	v_pk_mul_f32 v[112:113], v[116:117], v[180:181]
	v_pk_mul_f32 v[114:115], v[118:119], v[182:183]
	v_cvt_pk_bf16_f32 v116, v112, v113
	v_cvt_pk_bf16_f32 v117, v114, v115
	v_pk_mul_f32 v[114:115], v[120:121], v[178:179] op_sel_hi:[1,0]
	v_add_u32_e32 v112, 0x800, v179
	v_mul_f32_e32 v113, 0xbfb8aa3b, v114
	v_exp_f32_e32 v113, v113
	v_mul_f32_e32 v118, 0xbfb8aa3b, v115
	v_exp_f32_e32 v118, v118
	ds_write2_b64 v112, v[186:187], v[116:117] offset1:2
	v_add_f32_e32 v113, 1.0, v113
	v_rcp_f32_e32 v116, v113
	v_add_f32_e32 v113, 1.0, v118
	v_pk_mul_f32 v[118:119], v[122:123], v[178:179] op_sel_hi:[1,0]
	v_rcp_f32_e32 v117, v113
	v_mul_f32_e32 v113, 0xbfb8aa3b, v118
	v_exp_f32_e32 v113, v113
	v_mul_f32_e32 v120, 0xbfb8aa3b, v119
	v_exp_f32_e32 v120, v120
	v_pk_mul_f32 v[114:115], v[114:115], v[116:117]
	v_add_f32_e32 v113, 1.0, v113
	v_rcp_f32_e32 v116, v113
	v_add_f32_e32 v113, 1.0, v120
	v_pk_mul_f32 v[120:121], v[124:125], v[178:179] op_sel_hi:[1,0]
	v_rcp_f32_e32 v117, v113
	v_mul_f32_e32 v113, 0xbfb8aa3b, v120
	v_exp_f32_e32 v113, v113
	v_mul_f32_e32 v122, 0xbfb8aa3b, v121
	v_exp_f32_e32 v122, v122
	v_pk_mul_f32 v[116:117], v[118:119], v[116:117]
	v_add_f32_e32 v113, 1.0, v113
	v_rcp_f32_e32 v118, v113
	v_add_f32_e32 v113, 1.0, v122
	v_pk_mul_f32 v[122:123], v[126:127], v[178:179] op_sel_hi:[1,0]
	v_pk_mul_f32 v[96:97], v[96:97], v[178:179] op_sel_hi:[1,0]
	v_mul_f32_e32 v119, 0xbfb8aa3b, v122
	v_exp_f32_e32 v124, v119
	v_mul_f32_e32 v119, 0xbfb8aa3b, v123
	v_exp_f32_e32 v125, v119
	v_rcp_f32_e32 v119, v113
	v_add_f32_e32 v113, 1.0, v124
	v_rcp_f32_e32 v124, v113
	v_add_f32_e32 v113, 1.0, v125
	v_rcp_f32_e32 v125, v113
	v_cvt_pk_bf16_f32 v114, v114, v115
	v_cvt_pk_bf16_f32 v115, v116, v117
	v_pk_mul_f32 v[116:117], v[120:121], v[118:119]
	v_pk_mul_f32 v[118:119], v[122:123], v[124:125]
	v_mul_f32_e32 v113, 0xbfb8aa3b, v96
	v_cvt_pk_bf16_f32 v116, v116, v117
	v_cvt_pk_bf16_f32 v117, v118, v119
	v_exp_f32_e32 v113, v113
	v_mul_f32_e32 v118, 0xbfb8aa3b, v97
	v_exp_f32_e32 v118, v118
	ds_write2_b64 v112, v[114:115], v[116:117] offset0:4 offset1:6
	v_add_f32_e32 v113, 1.0, v113
	v_rcp_f32_e32 v114, v113
	v_add_f32_e32 v113, 1.0, v118
	v_pk_mul_f32 v[98:99], v[98:99], v[178:179] op_sel_hi:[1,0]
	v_rcp_f32_e32 v115, v113
	v_mul_f32_e32 v113, 0xbfb8aa3b, v98
; DI u32x2 pk4(float a, float b, float c, float d) { u32x2 r; r.x = pk2(a, b); r.y = pk2(c, d); return r; }
; DI float fsilu(float z) { return z * fsigmoid(z); }
; template <int WI, int WGJ, class GetF, class LdF, class FinF>
; DI void staged_rows_rmw(unsigned char* lds, int tid, GetF get, LdF ld, FinF fin) {
;     ...
;         unsigned char* wrow = lds + (wj * 32 + ln) * RS + (wi * WI * 32 + 4 * h) * 2;
; #pragma unroll
;         for (int it = 0; it < WI; ++it)
; #pragma unroll
;             for (int g = 0; g < 4; ++g) *(u32x2*)(wrow + (it * 32 + 8 * g) * 2) = get(it, jt, g);
; DI void phase3b(const Params& p, unsigned char* smem, int tid) {
;     ...
;                 [&](int it, int jt, int g) { const float sc = rsj[jt];
;                     return pk4(fsilu(acc[it][jt][4 * g] * sc), fsilu(acc[it][jt][4 * g + 1] * sc), fsilu(acc[it][jt][4 * g + 2] * sc), fsilu(acc[it][jt][4 * g + 3] * sc)); },
	v_exp_f32_e32 v113, v113
	v_mul_f32_e32 v116, 0xbfb8aa3b, v99
	v_exp_f32_e32 v116, v116
	v_pk_mul_f32 v[96:97], v[96:97], v[114:115]
	v_add_f32_e32 v113, 1.0, v113
	v_rcp_f32_e32 v114, v113
	v_add_f32_e32 v113, 1.0, v116
	v_pk_mul_f32 v[100:101], v[100:101], v[178:179] op_sel_hi:[1,0]
	v_rcp_f32_e32 v115, v113
	v_mul_f32_e32 v113, 0xbfb8aa3b, v100
	v_exp_f32_e32 v113, v113
	v_mul_f32_e32 v116, 0xbfb8aa3b, v101
	v_exp_f32_e32 v116, v116
	v_pk_mul_f32 v[102:103], v[102:103], v[178:179] op_sel_hi:[1,0]
	v_pk_mul_f32 v[98:99], v[98:99], v[114:115]
	v_add_f32_e32 v113, 1.0, v113
	v_mul_f32_e32 v115, 0xbfb8aa3b, v102
	v_rcp_f32_e32 v114, v113
	v_add_f32_e32 v113, 1.0, v116
	v_exp_f32_e32 v116, v115
	v_mul_f32_e32 v115, 0xbfb8aa3b, v103
	v_exp_f32_e32 v117, v115
	v_rcp_f32_e32 v115, v113
	v_add_f32_e32 v113, 1.0, v116
	v_rcp_f32_e32 v116, v113
	v_add_f32_e32 v113, 1.0, v117
	v_rcp_f32_e32 v117, v113
	v_cvt_pk_bf16_f32 v96, v96, v97
	v_cvt_pk_bf16_f32 v97, v98, v99
	v_pk_mul_f32 v[98:99], v[100:101], v[114:115]
	v_pk_mul_f32 v[100:101], v[102:103], v[116:117]
	v_cvt_pk_bf16_f32 v98, v98, v99
	v_cvt_pk_bf16_f32 v99, v100, v101
	v_pk_mul_f32 v[100:101], v[104:105], v[178:179] op_sel_hi:[1,0]
	ds_write2_b64 v112, v[96:97], v[98:99] offset0:8 offset1:10
	v_mul_f32_e32 v102, 0xbfb8aa3b, v100
	v_mul_f32_e32 v103, 0xbfb8aa3b, v101
	v_exp_f32_e32 v102, v102
	v_exp_f32_e32 v103, v103
	v_pk_mul_f32 v[98:99], v[106:107], v[178:179] op_sel_hi:[1,0]
	v_pk_mul_f32 v[80:81], v[80:81], v[178:179] op_sel_hi:[1,0]
	v_add_f32_e32 v96, 1.0, v102
	v_add_f32_e32 v97, 1.0, v103
	v_mul_f32_e32 v102, 0xbfb8aa3b, v98
	v_mul_f32_e32 v103, 0xbfb8aa3b, v99
	v_rcp_f32_e32 v96, v96
	v_rcp_f32_e32 v97, v97
	v_exp_f32_e32 v102, v102
	v_exp_f32_e32 v103, v103
	v_pk_mul_f32 v[82:83], v[82:83], v[178:179] op_sel_hi:[1,0]
	v_pk_mul_f32 v[96:97], v[100:101], v[96:97]
	v_add_f32_e32 v100, 1.0, v102
	v_add_f32_e32 v101, 1.0, v103
	v_pk_mul_f32 v[102:103], v[108:109], v[178:179] op_sel_hi:[1,0]
	v_rcp_f32_e32 v100, v100
	v_mul_f32_e32 v104, 0xbfb8aa3b, v102
	v_mul_f32_e32 v105, 0xbfb8aa3b, v103
	v_rcp_f32_e32 v101, v101
	v_exp_f32_e32 v104, v104
	v_exp_f32_e32 v105, v105
	v_cvt_pk_bf16_f32 v96, v96, v97
	v_pk_mul_f32 v[98:99], v[98:99], v[100:101]
	v_add_f32_e32 v100, 1.0, v104
	v_add_f32_e32 v101, 1.0, v105
	v_pk_mul_f32 v[104:105], v[110:111], v[178:179] op_sel_hi:[1,0]
	v_rcp_f32_e32 v100, v100
	v_mul_f32_e32 v106, 0xbfb8aa3b, v104
	v_mul_f32_e32 v107, 0xbfb8aa3b, v105
	v_exp_f32_e32 v106, v106
	v_exp_f32_e32 v107, v107
	v_rcp_f32_e32 v101, v101
	v_cvt_pk_bf16_f32 v97, v98, v99
	v_add_f32_e32 v106, 1.0, v106
	v_add_f32_e32 v107, 1.0, v107
	v_rcp_f32_e32 v106, v106
	v_rcp_f32_e32 v107, v107
	v_pk_mul_f32 v[98:99], v[102:103], v[100:101]
	v_pk_mul_f32 v[84:85], v[84:85], v[178:179] op_sel_hi:[1,0]
	v_cvt_pk_bf16_f32 v98, v98, v99
	v_pk_mul_f32 v[100:101], v[104:105], v[106:107]
	v_pk_mul_f32 v[86:87], v[86:87], v[178:179] op_sel_hi:[1,0]
	v_cvt_pk_bf16_f32 v99, v100, v101
	v_mul_f32_e32 v100, 0xbfb8aa3b, v80
	v_mul_f32_e32 v101, 0xbfb8aa3b, v81
	v_exp_f32_e32 v100, v100
	v_exp_f32_e32 v101, v101
	ds_write2_b64 v112, v[96:97], v[98:99] offset0:12 offset1:14
	v_mul_f32_e32 v98, 0xbfb8aa3b, v82
	v_add_f32_e32 v96, 1.0, v100
	v_add_f32_e32 v97, 1.0, v101
	v_mul_f32_e32 v99, 0xbfb8aa3b, v83
	v_rcp_f32_e32 v96, v96
	v_rcp_f32_e32 v97, v97
	v_exp_f32_e32 v98, v98
	v_exp_f32_e32 v99, v99
	v_pk_mul_f32 v[64:65], v[64:65], v[178:179] op_sel_hi:[1,0]
	v_pk_mul_f32 v[80:81], v[80:81], v[96:97]
	v_add_f32_e32 v96, 1.0, v98
	v_add_f32_e32 v97, 1.0, v99
	v_mul_f32_e32 v98, 0xbfb8aa3b, v84
	v_mul_f32_e32 v99, 0xbfb8aa3b, v85
	v_rcp_f32_e32 v96, v96
	v_rcp_f32_e32 v97, v97
	v_exp_f32_e32 v98, v98
	v_exp_f32_e32 v99, v99
	v_cvt_pk_bf16_f32 v80, v80, v81
	v_pk_mul_f32 v[82:83], v[82:83], v[96:97]
	v_add_f32_e32 v96, 1.0, v98
	v_add_f32_e32 v97, 1.0, v99
	v_mul_f32_e32 v98, 0xbfb8aa3b, v86
	v_mul_f32_e32 v99, 0xbfb8aa3b, v87
	v_exp_f32_e32 v98, v98
	v_exp_f32_e32 v99, v99
	v_rcp_f32_e32 v96, v96
	v_rcp_f32_e32 v97, v97
	v_add_f32_e32 v98, 1.0, v98
	v_add_f32_e32 v99, 1.0, v99
	v_rcp_f32_e32 v98, v98
	v_rcp_f32_e32 v99, v99
	v_cvt_pk_bf16_f32 v81, v82, v83
	v_pk_mul_f32 v[82:83], v[84:85], v[96:97]
	v_pk_mul_f32 v[66:67], v[66:67], v[178:179] op_sel_hi:[1,0]
	v_pk_mul_f32 v[84:85], v[86:87], v[98:99]
	v_cvt_pk_bf16_f32 v82, v82, v83
	v_cvt_pk_bf16_f32 v83, v84, v85
	v_pk_mul_f32 v[84:85], v[88:89], v[178:179] op_sel_hi:[1,0]
	ds_write2_b64 v112, v[80:81], v[82:83] offset0:16 offset1:18
	v_mul_f32_e32 v86, 0xbfb8aa3b, v84
	v_mul_f32_e32 v87, 0xbfb8aa3b, v85
	v_exp_f32_e32 v86, v86
	v_exp_f32_e32 v87, v87
	v_pk_mul_f32 v[82:83], v[90:91], v[178:179] op_sel_hi:[1,0]
	v_pk_mul_f32 v[68:69], v[68:69], v[178:179] op_sel_hi:[1,0]
	v_add_f32_e32 v80, 1.0, v86
	v_add_f32_e32 v81, 1.0, v87
	v_mul_f32_e32 v86, 0xbfb8aa3b, v82
	v_mul_f32_e32 v87, 0xbfb8aa3b, v83
	v_rcp_f32_e32 v80, v80
	v_rcp_f32_e32 v81, v81
	v_exp_f32_e32 v86, v86
	v_exp_f32_e32 v87, v87
	v_pk_mul_f32 v[70:71], v[70:71], v[178:179] op_sel_hi:[1,0]
	v_pk_mul_f32 v[80:81], v[84:85], v[80:81]
	v_add_f32_e32 v84, 1.0, v86
	v_add_f32_e32 v85, 1.0, v87
	v_pk_mul_f32 v[86:87], v[92:93], v[178:179] op_sel_hi:[1,0]
	v_rcp_f32_e32 v84, v84
	v_mul_f32_e32 v88, 0xbfb8aa3b, v86
	v_mul_f32_e32 v89, 0xbfb8aa3b, v87
	v_rcp_f32_e32 v85, v85
	v_exp_f32_e32 v88, v88
	v_exp_f32_e32 v89, v89
	v_cvt_pk_bf16_f32 v80, v80, v81
	v_pk_mul_f32 v[82:83], v[82:83], v[84:85]
	v_add_f32_e32 v84, 1.0, v88
	v_add_f32_e32 v85, 1.0, v89
	v_pk_mul_f32 v[88:89], v[94:95], v[178:179] op_sel_hi:[1,0]
	v_rcp_f32_e32 v84, v84
	v_mul_f32_e32 v90, 0xbfb8aa3b, v88
	v_mul_f32_e32 v91, 0xbfb8aa3b, v89
; DI unsigned pk2(float lo, float hi) { f32x2 v = {lo, hi}; bf2_t b = __builtin_convertvector(v, bf2_t); return __builtin_bit_cast(unsigned, b); }
; DI u32x2 pk4(float a, float b, float c, float d) { u32x2 r; r.x = pk2(a, b); r.y = pk2(c, d); return r; }
; DI float bf_lo(unsigned u) { return __uint_as_float(u << 16); }
; DI float bf_hi(unsigned u) { return __uint_as_float(u & 0xffff0000u); }
; DI float fsilu(float z) { return z * fsigmoid(z); }
; template <int WI, int WGJ, class GetF, class LdF, class FinF>
; DI void staged_rows_rmw(unsigned char* lds, int tid, GetF get, LdF ld, FinF fin) {
;     ...
;         __syncthreads();
; #pragma unroll 1
;         for (int gq = 0; gq < NGRP; ++gq) {
;             decltype(ld(0, 0)) fetched[GSZ];
; #pragma unroll
;             for (int c = 0; c < GSZ; ++c) {
;                 const int idx = tid + (gq * GSZ + c) * NT, lr = idx / NCH, ch = idx % NCH;
;                 fetched[c] = ld((lr >> 5) * 64 + jt * 32 + (lr & 31), ch * 8);
;             }
; #pragma unroll
;             for (int c = 0; c < GSZ; ++c) {
;                 const int idx = tid + (gq * GSZ + c) * NT, lr = idx / NCH, ch = idx % NCH;
;                 const u32x4 v = *(const u32x4*)(lds + lr * RS + ch * 16);
;                 fin((lr >> 5) * 64 + jt * 32 + (lr & 31), ch * 8, v, fetched[c]);
;             }
; DI void phase3b(const Params& p, unsigned char* smem, int tid) {
;     ...
;                 [&](int it, int jt, int g) { const float sc = rsj[jt];
;                     return pk4(fsilu(acc[it][jt][4 * g] * sc), fsilu(acc[it][jt][4 * g + 1] * sc), fsilu(acc[it][jt][4 * g + 2] * sc), fsilu(acc[it][jt][4 * g + 3] * sc)); },
;                 [&](int row, int col) { return *(const u32x4*)(obuf + (size_t)(r0 + row) * 1024 + col); },
;                 [&](int row, int col, u32x4 v, u32x4 o) { u32x4 w;
; #pragma unroll
;                     for (int e = 0; e < 4; ++e) w[e] = pk2(bf_lo(o[e]) * bf_lo(v[e]), bf_hi(o[e]) * bf_hi(v[e]));
;                     *(u32x4*)(obuf + (size_t)(r0 + row) * 1024 + col) = w; });
	v_exp_f32_e32 v90, v90
	v_exp_f32_e32 v91, v91
	v_rcp_f32_e32 v85, v85
	v_cvt_pk_bf16_f32 v81, v82, v83
	v_add_f32_e32 v90, 1.0, v90
	v_add_f32_e32 v91, 1.0, v91
	v_rcp_f32_e32 v90, v90
	v_rcp_f32_e32 v91, v91
	v_pk_mul_f32 v[82:83], v[86:87], v[84:85]
	s_lshr_b32 s22, s24, 2
	v_cvt_pk_bf16_f32 v82, v82, v83
	v_pk_mul_f32 v[84:85], v[88:89], v[90:91]
	s_cmp_lt_u32 s25, 4
	v_cvt_pk_bf16_f32 v83, v84, v85
	v_mul_f32_e32 v84, 0xbfb8aa3b, v64
	v_mul_f32_e32 v85, 0xbfb8aa3b, v65
	v_exp_f32_e32 v84, v84
	v_exp_f32_e32 v85, v85
	ds_write2_b64 v112, v[80:81], v[82:83] offset0:20 offset1:22
	v_mul_f32_e32 v82, 0xbfb8aa3b, v66
	v_add_f32_e32 v80, 1.0, v84
	v_add_f32_e32 v81, 1.0, v85
	v_mul_f32_e32 v83, 0xbfb8aa3b, v67
	v_rcp_f32_e32 v80, v80
	v_rcp_f32_e32 v81, v81
	v_exp_f32_e32 v82, v82
	v_exp_f32_e32 v83, v83
	s_cselect_b32 s23, s36, 0x398fc00
	v_pk_mul_f32 v[64:65], v[64:65], v[80:81]
	v_add_f32_e32 v80, 1.0, v82
	v_add_f32_e32 v81, 1.0, v83
	v_mul_f32_e32 v82, 0xbfb8aa3b, v68
	v_mul_f32_e32 v83, 0xbfb8aa3b, v69
	v_rcp_f32_e32 v80, v80
	v_rcp_f32_e32 v81, v81
	v_exp_f32_e32 v82, v82
	v_exp_f32_e32 v83, v83
	v_cvt_pk_bf16_f32 v64, v64, v65
	v_pk_mul_f32 v[66:67], v[66:67], v[80:81]
	v_add_f32_e32 v80, 1.0, v82
	v_add_f32_e32 v81, 1.0, v83
	v_mul_f32_e32 v82, 0xbfb8aa3b, v70
	v_mul_f32_e32 v83, 0xbfb8aa3b, v71
	v_exp_f32_e32 v82, v82
	v_exp_f32_e32 v83, v83
	v_rcp_f32_e32 v80, v80
	v_rcp_f32_e32 v81, v81
	v_add_f32_e32 v82, 1.0, v82
	v_add_f32_e32 v83, 1.0, v83
	v_rcp_f32_e32 v82, v82
	v_rcp_f32_e32 v83, v83
	v_cvt_pk_bf16_f32 v65, v66, v67
	v_pk_mul_f32 v[66:67], v[68:69], v[80:81]
	s_add_u32 s23, s56, s23
	v_pk_mul_f32 v[68:69], v[70:71], v[82:83]
	v_cvt_pk_bf16_f32 v66, v66, v67
	v_cvt_pk_bf16_f32 v67, v68, v69
	v_pk_mul_f32 v[68:69], v[72:73], v[178:179] op_sel_hi:[1,0]
	ds_write2_b64 v112, v[64:65], v[66:67] offset0:24 offset1:26
	v_mul_f32_e32 v70, 0xbfb8aa3b, v68
	v_mul_f32_e32 v71, 0xbfb8aa3b, v69
	v_exp_f32_e32 v70, v70
	v_exp_f32_e32 v71, v71
	v_pk_mul_f32 v[66:67], v[74:75], v[178:179] op_sel_hi:[1,0]
	s_addc_u32 s24, s57, 0
	v_add_f32_e32 v64, 1.0, v70
	v_add_f32_e32 v65, 1.0, v71
	v_mul_f32_e32 v70, 0xbfb8aa3b, v66
	v_mul_f32_e32 v71, 0xbfb8aa3b, v67
	v_rcp_f32_e32 v64, v64
	v_rcp_f32_e32 v65, v65
	v_exp_f32_e32 v70, v70
	v_exp_f32_e32 v71, v71
	s_lshl_b32 s22, s22, 9
	v_pk_mul_f32 v[64:65], v[68:69], v[64:65]
	v_add_f32_e32 v68, 1.0, v70
	v_add_f32_e32 v69, 1.0, v71
	v_pk_mul_f32 v[70:71], v[76:77], v[178:179] op_sel_hi:[1,0]
	v_rcp_f32_e32 v68, v68
	v_mul_f32_e32 v72, 0xbfb8aa3b, v70
	v_mul_f32_e32 v73, 0xbfb8aa3b, v71
	v_rcp_f32_e32 v69, v69
	v_exp_f32_e32 v72, v72
	v_exp_f32_e32 v73, v73
	s_and_b32 s22, s22, 0x600
	v_pk_mul_f32 v[66:67], v[66:67], v[68:69]
	v_add_f32_e32 v68, 1.0, v72
	v_add_f32_e32 v69, 1.0, v73
	v_pk_mul_f32 v[72:73], v[78:79], v[178:179] op_sel_hi:[1,0]
	v_rcp_f32_e32 v68, v68
	v_mul_f32_e32 v74, 0xbfb8aa3b, v72
	v_mul_f32_e32 v75, 0xbfb8aa3b, v73
	v_exp_f32_e32 v74, v74
	v_exp_f32_e32 v75, v75
	v_rcp_f32_e32 v69, v69
	s_add_u32 s22, s23, s22
	v_add_f32_e32 v74, 1.0, v74
	v_add_f32_e32 v75, 1.0, v75
	v_rcp_f32_e32 v74, v74
	v_rcp_f32_e32 v75, v75
	v_cvt_pk_bf16_f32 v64, v64, v65
	v_cvt_pk_bf16_f32 v65, v66, v67
	v_pk_mul_f32 v[66:67], v[70:71], v[68:69]
	v_pk_mul_f32 v[68:69], v[72:73], v[74:75]
	s_mov_b32 s14, 0
	s_addc_u32 s23, s24, 0
	v_cvt_pk_bf16_f32 v66, v66, v67
	v_cvt_pk_bf16_f32 v67, v68, v69
	s_mov_b64 s[24:25], -1
	ds_write2_b64 v112, v[64:65], v[66:67] offset0:28 offset1:30
	s_waitcnt lgkmcnt(0)
	s_barrier
	ds_read_b128 v[64:67], v197 offset:2048
	ds_read_b128 v[68:71], v197 offset:10496
	ds_read_b128 v[72:75], v197 offset:18944
	ds_read_b128 v[76:79], v197 offset:27392
	s_waitcnt lgkmcnt(3)
	v_lshlrev_b32_e32 v80, 16, v64
	v_and_b32_e32 v81, 0xffff0000, v64
	v_lshlrev_b32_e32 v82, 16, v65
	v_and_b32_e32 v83, 0xffff0000, v65
	v_lshlrev_b32_e32 v84, 16, v66
	v_and_b32_e32 v85, 0xffff0000, v66
	v_lshlrev_b32_e32 v86, 16, v67
	v_and_b32_e32 v87, 0xffff0000, v67
	s_waitcnt vmcnt(11)
	v_lshlrev_b32_e32 v88, 16, v188
	v_and_b32_e32 v89, 0xffff0000, v188
	v_lshlrev_b32_e32 v90, 16, v189
	v_and_b32_e32 v91, 0xffff0000, v189
	v_lshlrev_b32_e32 v92, 16, v190
	v_and_b32_e32 v93, 0xffff0000, v190
	v_lshlrev_b32_e32 v94, 16, v191
	v_and_b32_e32 v95, 0xffff0000, v191
	v_pk_mul_f32 v[88:89], v[88:89], v[80:81]
	v_pk_mul_f32 v[90:91], v[90:91], v[82:83]
	v_pk_mul_f32 v[92:93], v[92:93], v[84:85]
	v_pk_mul_f32 v[94:95], v[94:95], v[86:87]
	v_cvt_pk_bf16_f32 v188, v88, v89
	v_cvt_pk_bf16_f32 v189, v90, v91
	v_cvt_pk_bf16_f32 v190, v92, v93
	v_cvt_pk_bf16_f32 v191, v94, v95
	global_store_dwordx4 v196, v[188:191], s[100:101]
	s_waitcnt lgkmcnt(2)
	v_lshlrev_b32_e32 v80, 16, v68
	v_and_b32_e32 v81, 0xffff0000, v68
	v_lshlrev_b32_e32 v82, 16, v69
	v_and_b32_e32 v83, 0xffff0000, v69
	v_lshlrev_b32_e32 v84, 16, v70
	v_and_b32_e32 v85, 0xffff0000, v70
	v_lshlrev_b32_e32 v86, 16, v71
	v_and_b32_e32 v87, 0xffff0000, v71
	s_waitcnt vmcnt(11)
	v_lshlrev_b32_e32 v88, 16, v192
	v_and_b32_e32 v89, 0xffff0000, v192
	v_lshlrev_b32_e32 v90, 16, v193
	v_and_b32_e32 v91, 0xffff0000, v193
	v_lshlrev_b32_e32 v92, 16, v194
	v_and_b32_e32 v93, 0xffff0000, v194
	v_lshlrev_b32_e32 v94, 16, v195
	v_and_b32_e32 v95, 0xffff0000, v195
	v_pk_mul_f32 v[88:89], v[88:89], v[80:81]
	v_pk_mul_f32 v[90:91], v[90:91], v[82:83]
	v_pk_mul_f32 v[92:93], v[92:93], v[84:85]
	v_pk_mul_f32 v[94:95], v[94:95], v[86:87]
	v_cvt_pk_bf16_f32 v192, v88, v89
	v_cvt_pk_bf16_f32 v193, v90, v91
	v_cvt_pk_bf16_f32 v194, v92, v93
	v_cvt_pk_bf16_f32 v195, v94, v95
	v_add_u32_e32 v245, 0x8000, v196
	global_store_dwordx4 v245, v[192:195], s[100:101]
	s_waitcnt lgkmcnt(1)
; DI unsigned pk2(float lo, float hi) { f32x2 v = {lo, hi}; bf2_t b = __builtin_convertvector(v, bf2_t); return __builtin_bit_cast(unsigned, b); }
; DI float bf_lo(unsigned u) { return __uint_as_float(u << 16); }
; DI float bf_hi(unsigned u) { return __uint_as_float(u & 0xffff0000u); }
; template <int WI, int WGJ, class GetF, class LdF, class FinF>
; DI void staged_rows_rmw(unsigned char* lds, int tid, GetF get, LdF ld, FinF fin) {
;     ...
;         for (int gq = 0; gq < NGRP; ++gq) {
;             decltype(ld(0, 0)) fetched[GSZ];
; #pragma unroll
;             for (int c = 0; c < GSZ; ++c) {
;                 const int idx = tid + (gq * GSZ + c) * NT, lr = idx / NCH, ch = idx % NCH;
;                 fetched[c] = ld((lr >> 5) * 64 + jt * 32 + (lr & 31), ch * 8);
;             }
; #pragma unroll
;             for (int c = 0; c < GSZ; ++c) {
;                 const int idx = tid + (gq * GSZ + c) * NT, lr = idx / NCH, ch = idx % NCH;
;                 const u32x4 v = *(const u32x4*)(lds + lr * RS + ch * 16);
;                 fin((lr >> 5) * 64 + jt * 32 + (lr & 31), ch * 8, v, fetched[c]);
;             }
; DI void phase3b(const Params& p, unsigned char* smem, int tid) {
;     ...
;                 [&](int row, int col) { return *(const u32x4*)(obuf + (size_t)(r0 + row) * 1024 + col); },
;                 [&](int row, int col, u32x4 v, u32x4 o) { u32x4 w;
; #pragma unroll
;                     for (int e = 0; e < 4; ++e) w[e] = pk2(bf_lo(o[e]) * bf_lo(v[e]), bf_hi(o[e]) * bf_hi(v[e]));
;                     *(u32x4*)(obuf + (size_t)(r0 + row) * 1024 + col) = w; });
	v_lshlrev_b32_e32 v80, 16, v72
	v_and_b32_e32 v81, 0xffff0000, v72
	v_lshlrev_b32_e32 v82, 16, v73
	v_and_b32_e32 v83, 0xffff0000, v73
	v_lshlrev_b32_e32 v84, 16, v74
	v_and_b32_e32 v85, 0xffff0000, v74
	v_lshlrev_b32_e32 v86, 16, v75
	v_and_b32_e32 v87, 0xffff0000, v75
	s_waitcnt vmcnt(11)
	v_lshlrev_b32_e32 v88, 16, v200
	v_and_b32_e32 v89, 0xffff0000, v200
	v_lshlrev_b32_e32 v90, 16, v201
	v_and_b32_e32 v91, 0xffff0000, v201
	v_lshlrev_b32_e32 v92, 16, v202
	v_and_b32_e32 v93, 0xffff0000, v202
	v_lshlrev_b32_e32 v94, 16, v203
	v_and_b32_e32 v95, 0xffff0000, v203
	v_pk_mul_f32 v[88:89], v[88:89], v[80:81]
	v_pk_mul_f32 v[90:91], v[90:91], v[82:83]
	v_pk_mul_f32 v[92:93], v[92:93], v[84:85]
	v_pk_mul_f32 v[94:95], v[94:95], v[86:87]
	v_cvt_pk_bf16_f32 v200, v88, v89
	v_cvt_pk_bf16_f32 v201, v90, v91
	v_cvt_pk_bf16_f32 v202, v92, v93
	v_cvt_pk_bf16_f32 v203, v94, v95
	v_add_u32_e32 v244, 0x20000, v196
	global_store_dwordx4 v244, v[200:203], s[100:101]
	s_waitcnt lgkmcnt(0)
	v_lshlrev_b32_e32 v80, 16, v76
	v_and_b32_e32 v81, 0xffff0000, v76
	v_lshlrev_b32_e32 v82, 16, v77
	v_and_b32_e32 v83, 0xffff0000, v77
	v_lshlrev_b32_e32 v84, 16, v78
	v_and_b32_e32 v85, 0xffff0000, v78
	v_lshlrev_b32_e32 v86, 16, v79
	v_and_b32_e32 v87, 0xffff0000, v79
	s_waitcnt vmcnt(11)
	v_lshlrev_b32_e32 v88, 16, v204
	v_and_b32_e32 v89, 0xffff0000, v204
	v_lshlrev_b32_e32 v90, 16, v205
	v_and_b32_e32 v91, 0xffff0000, v205
	v_lshlrev_b32_e32 v92, 16, v206
	v_and_b32_e32 v93, 0xffff0000, v206
	v_lshlrev_b32_e32 v94, 16, v207
	v_and_b32_e32 v95, 0xffff0000, v207
	v_pk_mul_f32 v[88:89], v[88:89], v[80:81]
	v_pk_mul_f32 v[90:91], v[90:91], v[82:83]
	v_pk_mul_f32 v[92:93], v[92:93], v[84:85]
	v_pk_mul_f32 v[94:95], v[94:95], v[86:87]
	v_cvt_pk_bf16_f32 v204, v88, v89
	v_cvt_pk_bf16_f32 v205, v90, v91
	v_cvt_pk_bf16_f32 v206, v92, v93
	v_cvt_pk_bf16_f32 v207, v94, v95
	v_add_u32_e32 v245, 0x28000, v196
	global_store_dwordx4 v245, v[204:207], s[100:101]
	v_add_u32_e32 v244, 0x50000, v196
	global_load_dwordx4 v[188:191], v244, s[100:101]
	v_add_u32_e32 v245, 0x58000, v196
	global_load_dwordx4 v[192:195], v245, s[100:101]
	v_add_u32_e32 v244, 0x70000, v196
	global_load_dwordx4 v[200:203], v244, s[100:101]
	v_add_u32_e32 v245, 0x78000, v196
	global_load_dwordx4 v[204:207], v245, s[100:101]
	ds_read_b128 v[64:67], v197 offset:35840
	ds_read_b128 v[68:71], v197 offset:44288
	ds_read_b128 v[72:75], v197 offset:52736
	ds_read_b128 v[76:79], v197 offset:61184
	s_waitcnt lgkmcnt(3)
	v_lshlrev_b32_e32 v80, 16, v64
	v_and_b32_e32 v81, 0xffff0000, v64
	v_lshlrev_b32_e32 v82, 16, v65
	v_and_b32_e32 v83, 0xffff0000, v65
	v_lshlrev_b32_e32 v84, 16, v66
	v_and_b32_e32 v85, 0xffff0000, v66
	v_lshlrev_b32_e32 v86, 16, v67
	v_and_b32_e32 v87, 0xffff0000, v67
	s_waitcnt vmcnt(15)
	v_lshlrev_b32_e32 v88, 16, v208
	v_and_b32_e32 v89, 0xffff0000, v208
	v_lshlrev_b32_e32 v90, 16, v209
	v_and_b32_e32 v91, 0xffff0000, v209
	v_lshlrev_b32_e32 v92, 16, v210
	v_and_b32_e32 v93, 0xffff0000, v210
	v_lshlrev_b32_e32 v94, 16, v211
	v_and_b32_e32 v95, 0xffff0000, v211
	v_pk_mul_f32 v[88:89], v[88:89], v[80:81]
	v_pk_mul_f32 v[90:91], v[90:91], v[82:83]
	v_pk_mul_f32 v[92:93], v[92:93], v[84:85]
	v_pk_mul_f32 v[94:95], v[94:95], v[86:87]
	v_cvt_pk_bf16_f32 v208, v88, v89
	v_cvt_pk_bf16_f32 v209, v90, v91
	v_cvt_pk_bf16_f32 v210, v92, v93
	v_cvt_pk_bf16_f32 v211, v94, v95
	v_add_u32_e32 v244, 0x40000, v196
	global_store_dwordx4 v244, v[208:211], s[100:101]
	s_waitcnt lgkmcnt(2)
	v_lshlrev_b32_e32 v80, 16, v68
	v_and_b32_e32 v81, 0xffff0000, v68
	v_lshlrev_b32_e32 v82, 16, v69
	v_and_b32_e32 v83, 0xffff0000, v69
	v_lshlrev_b32_e32 v84, 16, v70
	v_and_b32_e32 v85, 0xffff0000, v70
	v_lshlrev_b32_e32 v86, 16, v71
	v_and_b32_e32 v87, 0xffff0000, v71
	s_waitcnt vmcnt(15)
	v_lshlrev_b32_e32 v88, 16, v212
	v_and_b32_e32 v89, 0xffff0000, v212
	v_lshlrev_b32_e32 v90, 16, v213
	v_and_b32_e32 v91, 0xffff0000, v213
	v_lshlrev_b32_e32 v92, 16, v214
	v_and_b32_e32 v93, 0xffff0000, v214
	v_lshlrev_b32_e32 v94, 16, v215
	v_and_b32_e32 v95, 0xffff0000, v215
	v_pk_mul_f32 v[88:89], v[88:89], v[80:81]
	v_pk_mul_f32 v[90:91], v[90:91], v[82:83]
	v_pk_mul_f32 v[92:93], v[92:93], v[84:85]
	v_pk_mul_f32 v[94:95], v[94:95], v[86:87]
	v_cvt_pk_bf16_f32 v212, v88, v89
	v_cvt_pk_bf16_f32 v213, v90, v91
	v_cvt_pk_bf16_f32 v214, v92, v93
	v_cvt_pk_bf16_f32 v215, v94, v95
	v_add_u32_e32 v245, 0x48000, v196
	global_store_dwordx4 v245, v[212:215], s[100:101]
	s_waitcnt lgkmcnt(1)
	v_lshlrev_b32_e32 v80, 16, v72
	v_and_b32_e32 v81, 0xffff0000, v72
	v_lshlrev_b32_e32 v82, 16, v73
	v_and_b32_e32 v83, 0xffff0000, v73
	v_lshlrev_b32_e32 v84, 16, v74
	v_and_b32_e32 v85, 0xffff0000, v74
	v_lshlrev_b32_e32 v86, 16, v75
	v_and_b32_e32 v87, 0xffff0000, v75
	s_waitcnt vmcnt(15)
	v_lshlrev_b32_e32 v88, 16, v216
	v_and_b32_e32 v89, 0xffff0000, v216
	v_lshlrev_b32_e32 v90, 16, v217
	v_and_b32_e32 v91, 0xffff0000, v217
	v_lshlrev_b32_e32 v92, 16, v218
	v_and_b32_e32 v93, 0xffff0000, v218
	v_lshlrev_b32_e32 v94, 16, v219
	v_and_b32_e32 v95, 0xffff0000, v219
	v_pk_mul_f32 v[88:89], v[88:89], v[80:81]
	v_pk_mul_f32 v[90:91], v[90:91], v[82:83]
	v_pk_mul_f32 v[92:93], v[92:93], v[84:85]
	v_pk_mul_f32 v[94:95], v[94:95], v[86:87]
	v_cvt_pk_bf16_f32 v216, v88, v89
	v_cvt_pk_bf16_f32 v217, v90, v91
	v_cvt_pk_bf16_f32 v218, v92, v93
	v_cvt_pk_bf16_f32 v219, v94, v95
	v_add_u32_e32 v244, 0x60000, v196
	global_store_dwordx4 v244, v[216:219], s[100:101]
	s_waitcnt lgkmcnt(0)
	v_lshlrev_b32_e32 v80, 16, v76
	v_and_b32_e32 v81, 0xffff0000, v76
	v_lshlrev_b32_e32 v82, 16, v77
	v_and_b32_e32 v83, 0xffff0000, v77
	v_lshlrev_b32_e32 v84, 16, v78
	v_and_b32_e32 v85, 0xffff0000, v78
	v_lshlrev_b32_e32 v86, 16, v79
	v_and_b32_e32 v87, 0xffff0000, v79
	s_waitcnt vmcnt(15)
; DI unsigned pk2(float lo, float hi) { f32x2 v = {lo, hi}; bf2_t b = __builtin_convertvector(v, bf2_t); return __builtin_bit_cast(unsigned, b); }
; DI float bf_lo(unsigned u) { return __uint_as_float(u << 16); }
; DI float bf_hi(unsigned u) { return __uint_as_float(u & 0xffff0000u); }
; template <int WI, int WGJ, class GetF, class LdF, class FinF>
; DI void staged_rows_rmw(unsigned char* lds, int tid, GetF get, LdF ld, FinF fin) {
;     ...
; #pragma unroll
;     for (int jt = 0; jt < 2; ++jt) {
;         unsigned char* wrow = lds + (wj * 32 + ln) * RS + (wi * WI * 32 + 4 * h) * 2;
; #pragma unroll
;         for (int it = 0; it < WI; ++it)
; #pragma unroll
;             for (int g = 0; g < 4; ++g) *(u32x2*)(wrow + (it * 32 + 8 * g) * 2) = get(it, jt, g);
;         constexpr int NGRP = 2, GSZ = NIT / NGRP;
;         __syncthreads();
; DI void phase3b(const Params& p, unsigned char* smem, int tid) {
;     ...
;                 [&](int row, int col) { return *(const u32x4*)(obuf + (size_t)(r0 + row) * 1024 + col); },
;                 [&](int row, int col, u32x4 v, u32x4 o) { u32x4 w;
; #pragma unroll
;                     for (int e = 0; e < 4; ++e) w[e] = pk2(bf_lo(o[e]) * bf_lo(v[e]), bf_hi(o[e]) * bf_hi(v[e]));
;                     *(u32x4*)(obuf + (size_t)(r0 + row) * 1024 + col) = w; });
	v_lshlrev_b32_e32 v88, 16, v220
	v_and_b32_e32 v89, 0xffff0000, v220
	v_lshlrev_b32_e32 v90, 16, v221
	v_and_b32_e32 v91, 0xffff0000, v221
	v_lshlrev_b32_e32 v92, 16, v222
	v_and_b32_e32 v93, 0xffff0000, v222
	v_lshlrev_b32_e32 v94, 16, v223
	v_and_b32_e32 v95, 0xffff0000, v223
	v_pk_mul_f32 v[88:89], v[88:89], v[80:81]
	v_pk_mul_f32 v[90:91], v[90:91], v[82:83]
	v_pk_mul_f32 v[92:93], v[92:93], v[84:85]
	v_pk_mul_f32 v[94:95], v[94:95], v[86:87]
	v_cvt_pk_bf16_f32 v220, v88, v89
	v_cvt_pk_bf16_f32 v221, v90, v91
	v_cvt_pk_bf16_f32 v222, v92, v93
	v_cvt_pk_bf16_f32 v223, v94, v95
	v_add_u32_e32 v245, 0x68000, v196
	global_store_dwordx4 v245, v[220:223], s[100:101]
	v_pk_mul_f32 v[48:49], v[48:49], v[176:177] op_sel_hi:[1,0]
	v_pk_mul_f32 v[50:51], v[50:51], v[176:177] op_sel_hi:[1,0]
	v_mul_f32_e32 v64, 0xbfb8aa3b, v48
	v_mul_f32_e32 v65, 0xbfb8aa3b, v49
	v_exp_f32_e32 v64, v64
	v_exp_f32_e32 v65, v65
	v_mul_f32_e32 v66, 0xbfb8aa3b, v50
	v_mul_f32_e32 v67, 0xbfb8aa3b, v51
	v_add_f32_e32 v64, 1.0, v64
	v_add_f32_e32 v65, 1.0, v65
	v_rcp_f32_e32 v64, v64
	v_rcp_f32_e32 v65, v65
	v_exp_f32_e32 v66, v66
	v_exp_f32_e32 v67, v67
	v_pk_mul_f32 v[52:53], v[52:53], v[176:177] op_sel_hi:[1,0]
	v_pk_mul_f32 v[48:49], v[48:49], v[64:65]
	v_add_f32_e32 v64, 1.0, v66
	v_add_f32_e32 v65, 1.0, v67
	v_mul_f32_e32 v66, 0xbfb8aa3b, v52
	v_mul_f32_e32 v67, 0xbfb8aa3b, v53
	v_rcp_f32_e32 v64, v64
	v_rcp_f32_e32 v65, v65
	v_exp_f32_e32 v66, v66
	v_exp_f32_e32 v67, v67
	v_pk_mul_f32 v[54:55], v[54:55], v[176:177] op_sel_hi:[1,0]
	v_pk_mul_f32 v[50:51], v[50:51], v[64:65]
	v_add_f32_e32 v64, 1.0, v66
	v_add_f32_e32 v65, 1.0, v67
	v_mul_f32_e32 v66, 0xbfb8aa3b, v54
	v_mul_f32_e32 v67, 0xbfb8aa3b, v55
	v_exp_f32_e32 v66, v66
	v_exp_f32_e32 v67, v67
	v_rcp_f32_e32 v64, v64
	v_rcp_f32_e32 v65, v65
	v_add_f32_e32 v66, 1.0, v66
	v_add_f32_e32 v67, 1.0, v67
	v_rcp_f32_e32 v66, v66
	v_rcp_f32_e32 v67, v67
	v_cvt_pk_bf16_f32 v48, v48, v49
	v_cvt_pk_bf16_f32 v49, v50, v51
	v_pk_mul_f32 v[50:51], v[52:53], v[64:65]
	v_pk_mul_f32 v[52:53], v[54:55], v[66:67]
	v_cvt_pk_bf16_f32 v50, v50, v51
	v_cvt_pk_bf16_f32 v51, v52, v53
	v_pk_mul_f32 v[52:53], v[56:57], v[176:177] op_sel_hi:[1,0]
	s_nop 0
	v_mul_f32_e32 v54, 0xbfb8aa3b, v52
	v_mul_f32_e32 v55, 0xbfb8aa3b, v53
	v_exp_f32_e32 v54, v54
	v_exp_f32_e32 v55, v55
	s_barrier
	ds_write2_b64 v112, v[48:49], v[50:51] offset1:2
	v_pk_mul_f32 v[50:51], v[58:59], v[176:177] op_sel_hi:[1,0]
	v_add_f32_e32 v48, 1.0, v54
	v_add_f32_e32 v49, 1.0, v55
	v_mul_f32_e32 v54, 0xbfb8aa3b, v50
	v_mul_f32_e32 v55, 0xbfb8aa3b, v51
	v_rcp_f32_e32 v48, v48
	v_rcp_f32_e32 v49, v49
	v_exp_f32_e32 v54, v54
	v_exp_f32_e32 v55, v55
	v_pk_mul_f32 v[32:33], v[32:33], v[176:177] op_sel_hi:[1,0]
	v_pk_mul_f32 v[48:49], v[52:53], v[48:49]
	v_add_f32_e32 v52, 1.0, v54
	v_add_f32_e32 v53, 1.0, v55
	v_pk_mul_f32 v[54:55], v[60:61], v[176:177] op_sel_hi:[1,0]
	v_rcp_f32_e32 v52, v52
	v_mul_f32_e32 v56, 0xbfb8aa3b, v54
	v_mul_f32_e32 v57, 0xbfb8aa3b, v55
	v_rcp_f32_e32 v53, v53
	v_exp_f32_e32 v56, v56
	v_exp_f32_e32 v57, v57
	v_cvt_pk_bf16_f32 v48, v48, v49
	v_pk_mul_f32 v[50:51], v[50:51], v[52:53]
	v_add_f32_e32 v52, 1.0, v56
	v_add_f32_e32 v53, 1.0, v57
	v_pk_mul_f32 v[56:57], v[62:63], v[176:177] op_sel_hi:[1,0]
	v_rcp_f32_e32 v52, v52
	v_mul_f32_e32 v58, 0xbfb8aa3b, v56
	v_mul_f32_e32 v59, 0xbfb8aa3b, v57
	v_exp_f32_e32 v58, v58
	v_exp_f32_e32 v59, v59
	v_rcp_f32_e32 v53, v53
	v_cvt_pk_bf16_f32 v49, v50, v51
	v_add_f32_e32 v58, 1.0, v58
	v_add_f32_e32 v59, 1.0, v59
	v_rcp_f32_e32 v58, v58
	v_rcp_f32_e32 v59, v59
	v_pk_mul_f32 v[50:51], v[54:55], v[52:53]
	v_pk_mul_f32 v[34:35], v[34:35], v[176:177] op_sel_hi:[1,0]
	v_cvt_pk_bf16_f32 v50, v50, v51
	v_pk_mul_f32 v[52:53], v[56:57], v[58:59]
	v_pk_mul_f32 v[36:37], v[36:37], v[176:177] op_sel_hi:[1,0]
	v_cvt_pk_bf16_f32 v51, v52, v53
	v_mul_f32_e32 v52, 0xbfb8aa3b, v32
	v_mul_f32_e32 v53, 0xbfb8aa3b, v33
	v_exp_f32_e32 v52, v52
	v_exp_f32_e32 v53, v53
	ds_write2_b64 v112, v[48:49], v[50:51] offset0:4 offset1:6
	v_mul_f32_e32 v50, 0xbfb8aa3b, v34
	v_add_f32_e32 v48, 1.0, v52
	v_add_f32_e32 v49, 1.0, v53
	v_mul_f32_e32 v51, 0xbfb8aa3b, v35
	v_rcp_f32_e32 v48, v48
	v_rcp_f32_e32 v49, v49
	v_exp_f32_e32 v50, v50
	v_exp_f32_e32 v51, v51
	v_pk_mul_f32 v[38:39], v[38:39], v[176:177] op_sel_hi:[1,0]
	v_pk_mul_f32 v[32:33], v[32:33], v[48:49]
	v_add_f32_e32 v48, 1.0, v50
	v_add_f32_e32 v49, 1.0, v51
	v_mul_f32_e32 v50, 0xbfb8aa3b, v36
	v_mul_f32_e32 v51, 0xbfb8aa3b, v37
	v_rcp_f32_e32 v48, v48
	v_rcp_f32_e32 v49, v49
	v_exp_f32_e32 v50, v50
	v_exp_f32_e32 v51, v51
	v_cvt_pk_bf16_f32 v32, v32, v33
	v_pk_mul_f32 v[34:35], v[34:35], v[48:49]
	v_add_f32_e32 v48, 1.0, v50
	v_add_f32_e32 v49, 1.0, v51
	v_mul_f32_e32 v50, 0xbfb8aa3b, v38
	v_mul_f32_e32 v51, 0xbfb8aa3b, v39
	v_exp_f32_e32 v50, v50
	v_exp_f32_e32 v51, v51
	v_rcp_f32_e32 v48, v48
	v_rcp_f32_e32 v49, v49
	v_add_f32_e32 v50, 1.0, v50
	v_add_f32_e32 v51, 1.0, v51
	v_rcp_f32_e32 v50, v50
	v_rcp_f32_e32 v51, v51
	v_cvt_pk_bf16_f32 v33, v34, v35
	v_pk_mul_f32 v[34:35], v[36:37], v[48:49]
	v_pk_mul_f32 v[16:17], v[16:17], v[176:177] op_sel_hi:[1,0]
	v_pk_mul_f32 v[36:37], v[38:39], v[50:51]
	v_cvt_pk_bf16_f32 v34, v34, v35
	v_cvt_pk_bf16_f32 v35, v36, v37
	v_pk_mul_f32 v[36:37], v[40:41], v[176:177] op_sel_hi:[1,0]
	ds_write2_b64 v112, v[32:33], v[34:35] offset0:8 offset1:10
	v_mul_f32_e32 v38, 0xbfb8aa3b, v36
	v_mul_f32_e32 v39, 0xbfb8aa3b, v37
	v_exp_f32_e32 v38, v38
	v_exp_f32_e32 v39, v39
	v_pk_mul_f32 v[34:35], v[42:43], v[176:177] op_sel_hi:[1,0]
	v_pk_mul_f32 v[18:19], v[18:19], v[176:177] op_sel_hi:[1,0]
	v_add_f32_e32 v32, 1.0, v38
	v_add_f32_e32 v33, 1.0, v39
; DI u32x2 pk4(float a, float b, float c, float d) { u32x2 r; r.x = pk2(a, b); r.y = pk2(c, d); return r; }
; DI float fsilu(float z) { return z * fsigmoid(z); }
; template <int WI, int WGJ, class GetF, class LdF, class FinF>
; DI void staged_rows_rmw(unsigned char* lds, int tid, GetF get, LdF ld, FinF fin) {
;     ...
;         unsigned char* wrow = lds + (wj * 32 + ln) * RS + (wi * WI * 32 + 4 * h) * 2;
; #pragma unroll
;         for (int it = 0; it < WI; ++it)
; #pragma unroll
;             for (int g = 0; g < 4; ++g) *(u32x2*)(wrow + (it * 32 + 8 * g) * 2) = get(it, jt, g);
; DI void phase3b(const Params& p, unsigned char* smem, int tid) {
;     ...
;                 [&](int it, int jt, int g) { const float sc = rsj[jt];
;                     return pk4(fsilu(acc[it][jt][4 * g] * sc), fsilu(acc[it][jt][4 * g + 1] * sc), fsilu(acc[it][jt][4 * g + 2] * sc), fsilu(acc[it][jt][4 * g + 3] * sc)); },
	v_mul_f32_e32 v38, 0xbfb8aa3b, v34
	v_mul_f32_e32 v39, 0xbfb8aa3b, v35
	v_rcp_f32_e32 v32, v32
	v_rcp_f32_e32 v33, v33
	v_exp_f32_e32 v38, v38
	v_exp_f32_e32 v39, v39
	v_pk_mul_f32 v[20:21], v[20:21], v[176:177] op_sel_hi:[1,0]
	v_pk_mul_f32 v[32:33], v[36:37], v[32:33]
	v_add_f32_e32 v36, 1.0, v38
	v_add_f32_e32 v37, 1.0, v39
	v_pk_mul_f32 v[38:39], v[44:45], v[176:177] op_sel_hi:[1,0]
	v_rcp_f32_e32 v36, v36
	v_mul_f32_e32 v40, 0xbfb8aa3b, v38
	v_mul_f32_e32 v41, 0xbfb8aa3b, v39
	v_rcp_f32_e32 v37, v37
	v_exp_f32_e32 v40, v40
	v_exp_f32_e32 v41, v41
	v_cvt_pk_bf16_f32 v32, v32, v33
	v_pk_mul_f32 v[34:35], v[34:35], v[36:37]
	v_add_f32_e32 v36, 1.0, v40
	v_add_f32_e32 v37, 1.0, v41
	v_pk_mul_f32 v[40:41], v[46:47], v[176:177] op_sel_hi:[1,0]
	v_rcp_f32_e32 v36, v36
	v_mul_f32_e32 v42, 0xbfb8aa3b, v40
	v_mul_f32_e32 v43, 0xbfb8aa3b, v41
	v_exp_f32_e32 v42, v42
	v_exp_f32_e32 v43, v43
	v_rcp_f32_e32 v37, v37
	v_cvt_pk_bf16_f32 v33, v34, v35
	v_add_f32_e32 v42, 1.0, v42
	v_add_f32_e32 v43, 1.0, v43
	v_rcp_f32_e32 v42, v42
	v_rcp_f32_e32 v43, v43
	v_pk_mul_f32 v[34:35], v[38:39], v[36:37]
	v_pk_mul_f32 v[22:23], v[22:23], v[176:177] op_sel_hi:[1,0]
	v_cvt_pk_bf16_f32 v34, v34, v35
	v_pk_mul_f32 v[36:37], v[40:41], v[42:43]
	v_pk_mul_f32 v[0:1], v[0:1], v[176:177] op_sel_hi:[1,0]
	v_cvt_pk_bf16_f32 v35, v36, v37
	v_mul_f32_e32 v36, 0xbfb8aa3b, v16
	v_mul_f32_e32 v37, 0xbfb8aa3b, v17
	v_exp_f32_e32 v36, v36
	v_exp_f32_e32 v37, v37
	ds_write2_b64 v112, v[32:33], v[34:35] offset0:12 offset1:14
	v_mul_f32_e32 v34, 0xbfb8aa3b, v18
	v_add_f32_e32 v32, 1.0, v36
	v_add_f32_e32 v33, 1.0, v37
	v_mul_f32_e32 v35, 0xbfb8aa3b, v19
	v_rcp_f32_e32 v32, v32
	v_rcp_f32_e32 v33, v33
	v_exp_f32_e32 v34, v34
	v_exp_f32_e32 v35, v35
	v_pk_mul_f32 v[2:3], v[2:3], v[176:177] op_sel_hi:[1,0]
	v_pk_mul_f32 v[16:17], v[16:17], v[32:33]
	v_add_f32_e32 v32, 1.0, v34
	v_add_f32_e32 v33, 1.0, v35
	v_mul_f32_e32 v34, 0xbfb8aa3b, v20
	v_mul_f32_e32 v35, 0xbfb8aa3b, v21
	v_rcp_f32_e32 v32, v32
	v_rcp_f32_e32 v33, v33
	v_exp_f32_e32 v34, v34
	v_exp_f32_e32 v35, v35
	v_cvt_pk_bf16_f32 v16, v16, v17
	v_pk_mul_f32 v[18:19], v[18:19], v[32:33]
	v_add_f32_e32 v32, 1.0, v34
	v_add_f32_e32 v33, 1.0, v35
	v_mul_f32_e32 v34, 0xbfb8aa3b, v22
	v_mul_f32_e32 v35, 0xbfb8aa3b, v23
	v_exp_f32_e32 v34, v34
	v_exp_f32_e32 v35, v35
	v_rcp_f32_e32 v32, v32
	v_rcp_f32_e32 v33, v33
	v_add_f32_e32 v34, 1.0, v34
	v_add_f32_e32 v35, 1.0, v35
	v_rcp_f32_e32 v34, v34
	v_rcp_f32_e32 v35, v35
	v_cvt_pk_bf16_f32 v17, v18, v19
	v_pk_mul_f32 v[18:19], v[20:21], v[32:33]
	v_pk_mul_f32 v[4:5], v[4:5], v[176:177] op_sel_hi:[1,0]
	v_pk_mul_f32 v[20:21], v[22:23], v[34:35]
	v_cvt_pk_bf16_f32 v18, v18, v19
	v_cvt_pk_bf16_f32 v19, v20, v21
	v_pk_mul_f32 v[20:21], v[24:25], v[176:177] op_sel_hi:[1,0]
	ds_write2_b64 v112, v[16:17], v[18:19] offset0:16 offset1:18
	v_mul_f32_e32 v22, 0xbfb8aa3b, v20
	v_mul_f32_e32 v23, 0xbfb8aa3b, v21
	v_exp_f32_e32 v22, v22
	v_exp_f32_e32 v23, v23
	v_pk_mul_f32 v[18:19], v[26:27], v[176:177] op_sel_hi:[1,0]
	v_pk_mul_f32 v[6:7], v[6:7], v[176:177] op_sel_hi:[1,0]
	v_add_f32_e32 v16, 1.0, v22
	v_add_f32_e32 v17, 1.0, v23
	v_mul_f32_e32 v22, 0xbfb8aa3b, v18
	v_mul_f32_e32 v23, 0xbfb8aa3b, v19
	v_rcp_f32_e32 v16, v16
	v_rcp_f32_e32 v17, v17
	v_exp_f32_e32 v22, v22
	v_exp_f32_e32 v23, v23
	s_add_i32 s26, s26, 32
	v_pk_mul_f32 v[16:17], v[20:21], v[16:17]
	v_add_f32_e32 v20, 1.0, v22
	v_add_f32_e32 v21, 1.0, v23
	v_pk_mul_f32 v[22:23], v[28:29], v[176:177] op_sel_hi:[1,0]
	v_rcp_f32_e32 v20, v20
	v_mul_f32_e32 v24, 0xbfb8aa3b, v22
	v_mul_f32_e32 v25, 0xbfb8aa3b, v23
	v_rcp_f32_e32 v21, v21
	v_exp_f32_e32 v24, v24
	v_exp_f32_e32 v25, v25
	v_cvt_pk_bf16_f32 v16, v16, v17
	v_pk_mul_f32 v[18:19], v[18:19], v[20:21]
	v_add_f32_e32 v20, 1.0, v24
	v_add_f32_e32 v21, 1.0, v25
	v_pk_mul_f32 v[24:25], v[30:31], v[176:177] op_sel_hi:[1,0]
	v_rcp_f32_e32 v20, v20
	v_mul_f32_e32 v26, 0xbfb8aa3b, v24
	v_mul_f32_e32 v27, 0xbfb8aa3b, v25
	v_exp_f32_e32 v26, v26
	v_exp_f32_e32 v27, v27
	v_rcp_f32_e32 v21, v21
	v_cvt_pk_bf16_f32 v17, v18, v19
	v_add_f32_e32 v26, 1.0, v26
	v_add_f32_e32 v27, 1.0, v27
	v_rcp_f32_e32 v26, v26
	v_rcp_f32_e32 v27, v27
	v_pk_mul_f32 v[18:19], v[22:23], v[20:21]
	s_mov_b32 s14, 0
	v_cvt_pk_bf16_f32 v18, v18, v19
	v_pk_mul_f32 v[20:21], v[24:25], v[26:27]
	s_mov_b64 s[24:25], -1
	v_cvt_pk_bf16_f32 v19, v20, v21
	v_mul_f32_e32 v20, 0xbfb8aa3b, v0
	v_mul_f32_e32 v21, 0xbfb8aa3b, v1
	v_exp_f32_e32 v20, v20
	v_exp_f32_e32 v21, v21
	ds_write2_b64 v112, v[16:17], v[18:19] offset0:20 offset1:22
	v_mul_f32_e32 v18, 0xbfb8aa3b, v2
	v_add_f32_e32 v16, 1.0, v20
	v_add_f32_e32 v17, 1.0, v21
	v_mul_f32_e32 v19, 0xbfb8aa3b, v3
	v_rcp_f32_e32 v16, v16
	v_rcp_f32_e32 v17, v17
	v_exp_f32_e32 v18, v18
	v_exp_f32_e32 v19, v19
	v_pk_mul_f32 v[0:1], v[0:1], v[16:17]
	v_add_f32_e32 v16, 1.0, v18
	v_add_f32_e32 v17, 1.0, v19
	v_mul_f32_e32 v18, 0xbfb8aa3b, v4
	v_mul_f32_e32 v19, 0xbfb8aa3b, v5
	v_rcp_f32_e32 v16, v16
	v_rcp_f32_e32 v17, v17
	v_exp_f32_e32 v18, v18
	v_exp_f32_e32 v19, v19
	v_cvt_pk_bf16_f32 v0, v0, v1
	v_pk_mul_f32 v[2:3], v[2:3], v[16:17]
	v_add_f32_e32 v16, 1.0, v18
	v_add_f32_e32 v17, 1.0, v19
	v_mul_f32_e32 v18, 0xbfb8aa3b, v6
	v_mul_f32_e32 v19, 0xbfb8aa3b, v7
	v_exp_f32_e32 v18, v18
	v_exp_f32_e32 v19, v19
	v_rcp_f32_e32 v16, v16
	v_rcp_f32_e32 v17, v17
	v_add_f32_e32 v18, 1.0, v18
	v_add_f32_e32 v19, 1.0, v19
	v_rcp_f32_e32 v18, v18
	v_rcp_f32_e32 v19, v19
	v_cvt_pk_bf16_f32 v1, v2, v3
	v_pk_mul_f32 v[2:3], v[4:5], v[16:17]
	v_pk_mul_f32 v[4:5], v[6:7], v[18:19]
	v_cvt_pk_bf16_f32 v2, v2, v3
	v_cvt_pk_bf16_f32 v3, v4, v5
	v_pk_mul_f32 v[4:5], v[8:9], v[176:177] op_sel_hi:[1,0]
; DI unsigned pk2(float lo, float hi) { f32x2 v = {lo, hi}; bf2_t b = __builtin_convertvector(v, bf2_t); return __builtin_bit_cast(unsigned, b); }
; DI float bf_lo(unsigned u) { return __uint_as_float(u << 16); }
; DI float bf_hi(unsigned u) { return __uint_as_float(u & 0xffff0000u); }
; template <int WI, int WGJ, class GetF, class LdF, class FinF>
; DI void staged_rows_rmw(unsigned char* lds, int tid, GetF get, LdF ld, FinF fin) {
;     ...
;         __syncthreads();
; #pragma unroll 1
;         for (int gq = 0; gq < NGRP; ++gq) {
;             decltype(ld(0, 0)) fetched[GSZ];
; #pragma unroll
;             for (int c = 0; c < GSZ; ++c) {
;                 const int idx = tid + (gq * GSZ + c) * NT, lr = idx / NCH, ch = idx % NCH;
;                 fetched[c] = ld((lr >> 5) * 64 + jt * 32 + (lr & 31), ch * 8);
;             }
; #pragma unroll
;             for (int c = 0; c < GSZ; ++c) {
;                 const int idx = tid + (gq * GSZ + c) * NT, lr = idx / NCH, ch = idx % NCH;
;                 const u32x4 v = *(const u32x4*)(lds + lr * RS + ch * 16);
;                 fin((lr >> 5) * 64 + jt * 32 + (lr & 31), ch * 8, v, fetched[c]);
;             }
; DI void phase3b(const Params& p, unsigned char* smem, int tid) {
;     ...
;                 [&](int row, int col) { return *(const u32x4*)(obuf + (size_t)(r0 + row) * 1024 + col); },
;                 [&](int row, int col, u32x4 v, u32x4 o) { u32x4 w;
; #pragma unroll
;                     for (int e = 0; e < 4; ++e) w[e] = pk2(bf_lo(o[e]) * bf_lo(v[e]), bf_hi(o[e]) * bf_hi(v[e]));
;                     *(u32x4*)(obuf + (size_t)(r0 + row) * 1024 + col) = w; });
	ds_write2_b64 v112, v[0:1], v[2:3] offset0:24 offset1:26
	v_mul_f32_e32 v6, 0xbfb8aa3b, v4
	v_mul_f32_e32 v7, 0xbfb8aa3b, v5
	v_exp_f32_e32 v6, v6
	v_exp_f32_e32 v7, v7
	v_pk_mul_f32 v[2:3], v[10:11], v[176:177] op_sel_hi:[1,0]
	v_add_f32_e32 v0, 1.0, v6
	v_add_f32_e32 v1, 1.0, v7
	v_mul_f32_e32 v6, 0xbfb8aa3b, v2
	v_mul_f32_e32 v7, 0xbfb8aa3b, v3
	v_rcp_f32_e32 v0, v0
	v_rcp_f32_e32 v1, v1
	v_exp_f32_e32 v6, v6
	v_exp_f32_e32 v7, v7
	v_pk_mul_f32 v[0:1], v[4:5], v[0:1]
	v_add_f32_e32 v4, 1.0, v6
	v_add_f32_e32 v5, 1.0, v7
	v_pk_mul_f32 v[6:7], v[12:13], v[176:177] op_sel_hi:[1,0]
	v_rcp_f32_e32 v4, v4
	v_mul_f32_e32 v8, 0xbfb8aa3b, v6
	v_mul_f32_e32 v9, 0xbfb8aa3b, v7
	v_rcp_f32_e32 v5, v5
	v_exp_f32_e32 v8, v8
	v_exp_f32_e32 v9, v9
	v_cvt_pk_bf16_f32 v0, v0, v1
	v_pk_mul_f32 v[2:3], v[2:3], v[4:5]
	v_add_f32_e32 v4, 1.0, v8
	v_add_f32_e32 v5, 1.0, v9
	v_pk_mul_f32 v[8:9], v[14:15], v[176:177] op_sel_hi:[1,0]
	v_rcp_f32_e32 v4, v4
	v_mul_f32_e32 v10, 0xbfb8aa3b, v8
	v_mul_f32_e32 v11, 0xbfb8aa3b, v9
	v_exp_f32_e32 v10, v10
	v_exp_f32_e32 v11, v11
	v_rcp_f32_e32 v5, v5
	v_cvt_pk_bf16_f32 v1, v2, v3
	v_add_f32_e32 v10, 1.0, v10
	v_add_f32_e32 v11, 1.0, v11
	v_rcp_f32_e32 v10, v10
	v_rcp_f32_e32 v11, v11
	v_pk_mul_f32 v[2:3], v[6:7], v[4:5]
	v_pk_mul_f32 v[4:5], v[8:9], v[10:11]
	v_cvt_pk_bf16_f32 v2, v2, v3
	v_cvt_pk_bf16_f32 v3, v4, v5
	ds_write2_b64 v112, v[0:1], v[2:3] offset0:28 offset1:30
	s_waitcnt lgkmcnt(0)
	s_barrier
	ds_read_b128 v[64:67], v197 offset:2048
	ds_read_b128 v[68:71], v197 offset:10496
	ds_read_b128 v[72:75], v197 offset:18944
	ds_read_b128 v[76:79], v197 offset:27392
	s_waitcnt lgkmcnt(3)
	v_lshlrev_b32_e32 v80, 16, v64
	v_and_b32_e32 v81, 0xffff0000, v64
	v_lshlrev_b32_e32 v82, 16, v65
	v_and_b32_e32 v83, 0xffff0000, v65
	v_lshlrev_b32_e32 v84, 16, v66
	v_and_b32_e32 v85, 0xffff0000, v66
	v_lshlrev_b32_e32 v86, 16, v67
	v_and_b32_e32 v87, 0xffff0000, v67
	s_waitcnt vmcnt(15)
	v_lshlrev_b32_e32 v88, 16, v224
	v_and_b32_e32 v89, 0xffff0000, v224
	v_lshlrev_b32_e32 v90, 16, v225
	v_and_b32_e32 v91, 0xffff0000, v225
	v_lshlrev_b32_e32 v92, 16, v226
	v_and_b32_e32 v93, 0xffff0000, v226
	v_lshlrev_b32_e32 v94, 16, v227
	v_and_b32_e32 v95, 0xffff0000, v227
	v_pk_mul_f32 v[88:89], v[88:89], v[80:81]
	v_pk_mul_f32 v[90:91], v[90:91], v[82:83]
	v_pk_mul_f32 v[92:93], v[92:93], v[84:85]
	v_pk_mul_f32 v[94:95], v[94:95], v[86:87]
	v_cvt_pk_bf16_f32 v224, v88, v89
	v_cvt_pk_bf16_f32 v225, v90, v91
	v_cvt_pk_bf16_f32 v226, v92, v93
	v_cvt_pk_bf16_f32 v227, v94, v95
	v_add_u32_e32 v244, 0x10000, v196
	global_store_dwordx4 v244, v[224:227], s[100:101]
	s_waitcnt lgkmcnt(2)
	v_lshlrev_b32_e32 v80, 16, v68
	v_and_b32_e32 v81, 0xffff0000, v68
	v_lshlrev_b32_e32 v82, 16, v69
	v_and_b32_e32 v83, 0xffff0000, v69
	v_lshlrev_b32_e32 v84, 16, v70
	v_and_b32_e32 v85, 0xffff0000, v70
	v_lshlrev_b32_e32 v86, 16, v71
	v_and_b32_e32 v87, 0xffff0000, v71
	s_waitcnt vmcnt(15)
	v_lshlrev_b32_e32 v88, 16, v228
	v_and_b32_e32 v89, 0xffff0000, v228
	v_lshlrev_b32_e32 v90, 16, v229
	v_and_b32_e32 v91, 0xffff0000, v229
	v_lshlrev_b32_e32 v92, 16, v230
	v_and_b32_e32 v93, 0xffff0000, v230
	v_lshlrev_b32_e32 v94, 16, v231
	v_and_b32_e32 v95, 0xffff0000, v231
	v_pk_mul_f32 v[88:89], v[88:89], v[80:81]
	v_pk_mul_f32 v[90:91], v[90:91], v[82:83]
	v_pk_mul_f32 v[92:93], v[92:93], v[84:85]
	v_pk_mul_f32 v[94:95], v[94:95], v[86:87]
	v_cvt_pk_bf16_f32 v228, v88, v89
	v_cvt_pk_bf16_f32 v229, v90, v91
	v_cvt_pk_bf16_f32 v230, v92, v93
	v_cvt_pk_bf16_f32 v231, v94, v95
	v_add_u32_e32 v245, 0x18000, v196
	global_store_dwordx4 v245, v[228:231], s[100:101]
	s_waitcnt lgkmcnt(1)
	v_lshlrev_b32_e32 v80, 16, v72
	v_and_b32_e32 v81, 0xffff0000, v72
	v_lshlrev_b32_e32 v82, 16, v73
	v_and_b32_e32 v83, 0xffff0000, v73
	v_lshlrev_b32_e32 v84, 16, v74
	v_and_b32_e32 v85, 0xffff0000, v74
	v_lshlrev_b32_e32 v86, 16, v75
	v_and_b32_e32 v87, 0xffff0000, v75
	s_waitcnt vmcnt(15)
	v_lshlrev_b32_e32 v88, 16, v232
	v_and_b32_e32 v89, 0xffff0000, v232
	v_lshlrev_b32_e32 v90, 16, v233
	v_and_b32_e32 v91, 0xffff0000, v233
	v_lshlrev_b32_e32 v92, 16, v234
	v_and_b32_e32 v93, 0xffff0000, v234
	v_lshlrev_b32_e32 v94, 16, v235
	v_and_b32_e32 v95, 0xffff0000, v235
	v_pk_mul_f32 v[88:89], v[88:89], v[80:81]
	v_pk_mul_f32 v[90:91], v[90:91], v[82:83]
	v_pk_mul_f32 v[92:93], v[92:93], v[84:85]
	v_pk_mul_f32 v[94:95], v[94:95], v[86:87]
	v_cvt_pk_bf16_f32 v232, v88, v89
	v_cvt_pk_bf16_f32 v233, v90, v91
	v_cvt_pk_bf16_f32 v234, v92, v93
	v_cvt_pk_bf16_f32 v235, v94, v95
	v_add_u32_e32 v244, 0x30000, v196
	global_store_dwordx4 v244, v[232:235], s[100:101]
	s_waitcnt lgkmcnt(0)
	v_lshlrev_b32_e32 v80, 16, v76
	v_and_b32_e32 v81, 0xffff0000, v76
	v_lshlrev_b32_e32 v82, 16, v77
	v_and_b32_e32 v83, 0xffff0000, v77
	v_lshlrev_b32_e32 v84, 16, v78
	v_and_b32_e32 v85, 0xffff0000, v78
	v_lshlrev_b32_e32 v86, 16, v79
	v_and_b32_e32 v87, 0xffff0000, v79
	s_waitcnt vmcnt(15)
; DI unsigned pk2(float lo, float hi) { f32x2 v = {lo, hi}; bf2_t b = __builtin_convertvector(v, bf2_t); return __builtin_bit_cast(unsigned, b); }
; DI float bf_lo(unsigned u) { return __uint_as_float(u << 16); }
; DI float bf_hi(unsigned u) { return __uint_as_float(u & 0xffff0000u); }
; template <int WI, int WGJ, class GetF, class LdF, class FinF>
; DI void staged_rows_rmw(unsigned char* lds, int tid, GetF get, LdF ld, FinF fin) {
;     ...
;             for (int c = 0; c < GSZ; ++c) {
;                 const int idx = tid + (gq * GSZ + c) * NT, lr = idx / NCH, ch = idx % NCH;
;                 fetched[c] = ld((lr >> 5) * 64 + jt * 32 + (lr & 31), ch * 8);
;             }
; #pragma unroll
;             for (int c = 0; c < GSZ; ++c) {
;                 const int idx = tid + (gq * GSZ + c) * NT, lr = idx / NCH, ch = idx % NCH;
;                 const u32x4 v = *(const u32x4*)(lds + lr * RS + ch * 16);
;                 fin((lr >> 5) * 64 + jt * 32 + (lr & 31), ch * 8, v, fetched[c]);
;             }
;         }
;         __syncthreads();
; DI void phase3b(const Params& p, unsigned char* smem, int tid) {
;     ...
;                 [&](int row, int col) { return *(const u32x4*)(obuf + (size_t)(r0 + row) * 1024 + col); },
;                 [&](int row, int col, u32x4 v, u32x4 o) { u32x4 w;
; #pragma unroll
;                     for (int e = 0; e < 4; ++e) w[e] = pk2(bf_lo(o[e]) * bf_lo(v[e]), bf_hi(o[e]) * bf_hi(v[e]));
;                     *(u32x4*)(obuf + (size_t)(r0 + row) * 1024 + col) = w; });
	v_lshlrev_b32_e32 v88, 16, v236
	v_and_b32_e32 v89, 0xffff0000, v236
	v_lshlrev_b32_e32 v90, 16, v237
	v_and_b32_e32 v91, 0xffff0000, v237
	v_lshlrev_b32_e32 v92, 16, v238
	v_and_b32_e32 v93, 0xffff0000, v238
	v_lshlrev_b32_e32 v94, 16, v239
	v_and_b32_e32 v95, 0xffff0000, v239
	v_pk_mul_f32 v[88:89], v[88:89], v[80:81]
	v_pk_mul_f32 v[90:91], v[90:91], v[82:83]
	v_pk_mul_f32 v[92:93], v[92:93], v[84:85]
	v_pk_mul_f32 v[94:95], v[94:95], v[86:87]
	v_cvt_pk_bf16_f32 v236, v88, v89
	v_cvt_pk_bf16_f32 v237, v90, v91
	v_cvt_pk_bf16_f32 v238, v92, v93
	v_cvt_pk_bf16_f32 v239, v94, v95
	v_add_u32_e32 v245, 0x38000, v196
	global_store_dwordx4 v245, v[236:239], s[100:101]
	ds_read_b128 v[64:67], v197 offset:35840
	ds_read_b128 v[68:71], v197 offset:44288
	ds_read_b128 v[72:75], v197 offset:52736
	ds_read_b128 v[76:79], v197 offset:61184
	s_waitcnt lgkmcnt(3)
	v_lshlrev_b32_e32 v80, 16, v64
	v_and_b32_e32 v81, 0xffff0000, v64
	v_lshlrev_b32_e32 v82, 16, v65
	v_and_b32_e32 v83, 0xffff0000, v65
	v_lshlrev_b32_e32 v84, 16, v66
	v_and_b32_e32 v85, 0xffff0000, v66
	v_lshlrev_b32_e32 v86, 16, v67
	v_and_b32_e32 v87, 0xffff0000, v67
	s_waitcnt vmcnt(11)
	v_lshlrev_b32_e32 v88, 16, v188
	v_and_b32_e32 v89, 0xffff0000, v188
	v_lshlrev_b32_e32 v90, 16, v189
	v_and_b32_e32 v91, 0xffff0000, v189
	v_lshlrev_b32_e32 v92, 16, v190
	v_and_b32_e32 v93, 0xffff0000, v190
	v_lshlrev_b32_e32 v94, 16, v191
	v_and_b32_e32 v95, 0xffff0000, v191
	v_pk_mul_f32 v[88:89], v[88:89], v[80:81]
	v_pk_mul_f32 v[90:91], v[90:91], v[82:83]
	v_pk_mul_f32 v[92:93], v[92:93], v[84:85]
	v_pk_mul_f32 v[94:95], v[94:95], v[86:87]
	v_cvt_pk_bf16_f32 v188, v88, v89
	v_cvt_pk_bf16_f32 v189, v90, v91
	v_cvt_pk_bf16_f32 v190, v92, v93
	v_cvt_pk_bf16_f32 v191, v94, v95
	v_add_u32_e32 v244, 0x50000, v196
	global_store_dwordx4 v244, v[188:191], s[100:101]
	s_waitcnt lgkmcnt(2)
	v_lshlrev_b32_e32 v80, 16, v68
	v_and_b32_e32 v81, 0xffff0000, v68
	v_lshlrev_b32_e32 v82, 16, v69
	v_and_b32_e32 v83, 0xffff0000, v69
	v_lshlrev_b32_e32 v84, 16, v70
	v_and_b32_e32 v85, 0xffff0000, v70
	v_lshlrev_b32_e32 v86, 16, v71
	v_and_b32_e32 v87, 0xffff0000, v71
	s_waitcnt vmcnt(11)
	v_lshlrev_b32_e32 v88, 16, v192
	v_and_b32_e32 v89, 0xffff0000, v192
	v_lshlrev_b32_e32 v90, 16, v193
	v_and_b32_e32 v91, 0xffff0000, v193
	v_lshlrev_b32_e32 v92, 16, v194
	v_and_b32_e32 v93, 0xffff0000, v194
	v_lshlrev_b32_e32 v94, 16, v195
	v_and_b32_e32 v95, 0xffff0000, v195
	v_pk_mul_f32 v[88:89], v[88:89], v[80:81]
	v_pk_mul_f32 v[90:91], v[90:91], v[82:83]
	v_pk_mul_f32 v[92:93], v[92:93], v[84:85]
	v_pk_mul_f32 v[94:95], v[94:95], v[86:87]
	v_cvt_pk_bf16_f32 v192, v88, v89
	v_cvt_pk_bf16_f32 v193, v90, v91
	v_cvt_pk_bf16_f32 v194, v92, v93
	v_cvt_pk_bf16_f32 v195, v94, v95
	v_add_u32_e32 v245, 0x58000, v196
	global_store_dwordx4 v245, v[192:195], s[100:101]
	s_waitcnt lgkmcnt(1)
	v_lshlrev_b32_e32 v80, 16, v72
	v_and_b32_e32 v81, 0xffff0000, v72
	v_lshlrev_b32_e32 v82, 16, v73
	v_and_b32_e32 v83, 0xffff0000, v73
	v_lshlrev_b32_e32 v84, 16, v74
	v_and_b32_e32 v85, 0xffff0000, v74
	v_lshlrev_b32_e32 v86, 16, v75
	v_and_b32_e32 v87, 0xffff0000, v75
	s_waitcnt vmcnt(11)
	v_lshlrev_b32_e32 v88, 16, v200
	v_and_b32_e32 v89, 0xffff0000, v200
	v_lshlrev_b32_e32 v90, 16, v201
	v_and_b32_e32 v91, 0xffff0000, v201
	v_lshlrev_b32_e32 v92, 16, v202
	v_and_b32_e32 v93, 0xffff0000, v202
	v_lshlrev_b32_e32 v94, 16, v203
	v_and_b32_e32 v95, 0xffff0000, v203
	v_pk_mul_f32 v[88:89], v[88:89], v[80:81]
	v_pk_mul_f32 v[90:91], v[90:91], v[82:83]
	v_pk_mul_f32 v[92:93], v[92:93], v[84:85]
	v_pk_mul_f32 v[94:95], v[94:95], v[86:87]
	v_cvt_pk_bf16_f32 v200, v88, v89
	v_cvt_pk_bf16_f32 v201, v90, v91
	v_cvt_pk_bf16_f32 v202, v92, v93
	v_cvt_pk_bf16_f32 v203, v94, v95
	v_add_u32_e32 v244, 0x70000, v196
	global_store_dwordx4 v244, v[200:203], s[100:101]
	s_waitcnt lgkmcnt(0)
	v_lshlrev_b32_e32 v80, 16, v76
	v_and_b32_e32 v81, 0xffff0000, v76
	v_lshlrev_b32_e32 v82, 16, v77
	v_and_b32_e32 v83, 0xffff0000, v77
	v_lshlrev_b32_e32 v84, 16, v78
	v_and_b32_e32 v85, 0xffff0000, v78
	v_lshlrev_b32_e32 v86, 16, v79
	v_and_b32_e32 v87, 0xffff0000, v79
	s_waitcnt vmcnt(11)
	v_lshlrev_b32_e32 v88, 16, v204
	v_and_b32_e32 v89, 0xffff0000, v204
	v_lshlrev_b32_e32 v90, 16, v205
	v_and_b32_e32 v91, 0xffff0000, v205
	v_lshlrev_b32_e32 v92, 16, v206
	v_and_b32_e32 v93, 0xffff0000, v206
	v_lshlrev_b32_e32 v94, 16, v207
	v_and_b32_e32 v95, 0xffff0000, v207
	v_pk_mul_f32 v[88:89], v[88:89], v[80:81]
	v_pk_mul_f32 v[90:91], v[90:91], v[82:83]
	v_pk_mul_f32 v[92:93], v[92:93], v[84:85]
	v_pk_mul_f32 v[94:95], v[94:95], v[86:87]
	v_cvt_pk_bf16_f32 v204, v88, v89
	v_cvt_pk_bf16_f32 v205, v90, v91
	v_cvt_pk_bf16_f32 v206, v92, v93
	v_cvt_pk_bf16_f32 v207, v94, v95
	v_add_u32_e32 v245, 0x78000, v196
	global_store_dwordx4 v245, v[204:207], s[100:101]
	s_barrier
	s_branch .LBB0_912
